# v5 + FFT big-path stage 1: second-tile twiddle loads issued half a tile earlier into free registers
# speedup vs baseline: 1.0465x; 1.0016x over previous
.LBB0_555:
	v_add_u32_e32 v85, 0, v84
	ds_read_b64_tr_b16 v[86:87], v85
	ds_read_b64_tr_b16 v[88:89], v85 offset:1088
	ds_read_b64_tr_b16 v[120:121], v85 offset:34816
	s_waitcnt vmcnt(1)
	ds_read_b64_tr_b16 v[122:123], v85 offset:35904
	v_mov_b32_e32 v82, v118
	v_mov_b32_e32 v83, v112
	s_waitcnt lgkmcnt(2)
	v_mfma_f32_16x16x32_f16 v[124:127], v[54:57], v[86:89], 0
	v_mov_b32_e32 v112, v119
	v_mov_b32_e32 v136, v116
	s_waitcnt vmcnt(0)
	v_mov_b32_e32 v137, v114
	s_waitcnt vmcnt(0) lgkmcnt(0)
	v_mfma_f32_16x16x32_f16 v[128:131], v[54:57], v[120:123], 0
	v_mov_b32_e32 v114, v117
	s_min_i32 s10, s1, 6
	v_add_u32_e32 v111, s20, v184
	v_mfma_f32_16x16x32_f16 v[120:123], v[50:53], v[120:123], v[124:127]
	v_add_u32_e32 v213, 0, v0
	v_add_u32_e32 v214, 0x190, v111
	v_add_u32_e32 v217, 0x19800, v213
	ds_read_b64_tr_b16 v[124:125], v85 offset:8704
	ds_read_b64_tr_b16 v[126:127], v85 offset:9792
	ds_read_b64_tr_b16 v[118:119], v85 offset:43520
	v_mfma_f32_16x16x32_f16 v[86:89], v[2:5], v[86:89], v[128:131]
	v_ashrrev_i32_e32 v215, 31, v214
	s_add_i32 s1, s1, 2
	s_add_i32 s20, s20, 32
	s_waitcnt lgkmcnt(1)
	v_mfma_f32_16x16x32_f16 v[128:131], v[46:49], v[124:127], v[120:123]
	v_add_u32_e32 v84, 64, v84
	v_add_u32_e32 v0, 0x2200, v0
	s_cmpk_eq_i32 s20, 0x80
	ds_read_b64_tr_b16 v[120:121], v85 offset:44608
	s_waitcnt lgkmcnt(0)
	v_mfma_f32_16x16x32_f16 v[86:89], v[46:49], v[118:121], v[86:89]
	v_mfma_f32_16x16x32_f16 v[116:119], v[42:45], v[118:121], v[128:131]
	ds_read_b64_tr_b16 v[120:121], v85 offset:17408
	v_mfma_f32_16x16x32_f16 v[86:89], v[6:9], v[124:127], v[86:89]
	ds_read_b64_tr_b16 v[122:123], v85 offset:18496
	ds_read_b64_tr_b16 v[124:125], v85 offset:52224
	ds_read_b64_tr_b16 v[126:127], v85 offset:53312
	ds_read_b64_tr_b16 v[128:129], v85 offset:26112
	ds_read_b64_tr_b16 v[130:131], v85 offset:27200
	ds_read_b64_tr_b16 v[132:133], v85 offset:60928
	ds_read_b64_tr_b16 v[134:135], v85 offset:62016
	s_waitcnt lgkmcnt(4)
	v_mfma_f32_16x16x32_f16 v[86:89], v[38:41], v[124:127], v[86:89]
	v_mfma_f32_16x16x32_f16 v[116:119], v[38:41], v[120:123], v[116:119]
	v_mfma_f32_16x16x32_f16 v[86:89], v[10:13], v[120:123], v[86:89]
	v_lshl_add_u32 v120, s10, 4, v140
	v_or_b32_e32 v216, v120, v141
	v_add_u32_e32 v218, v174, v120
	v_mfma_f32_16x16x32_f16 v[116:119], v[34:37], v[124:127], v[116:119]
	v_add_u32_e32 v220, v175, v120
	v_add_u32_e32 v124, 16, v111
	v_add_u32_e32 v126, 0x90, v111
	s_waitcnt lgkmcnt(0)
	v_mfma_f32_16x16x32_f16 v[86:89], v[30:33], v[132:135], v[86:89]
	v_add_u32_e32 v111, 0x11000, v213
	v_ashrrev_i32_e32 v125, 31, v124
	v_ashrrev_i32_e32 v127, 31, v126
	v_mfma_f32_16x16x32_f16 v[116:119], v[30:33], v[128:131], v[116:119]
	v_lshl_add_u64 v[124:125], v[124:125], 3, s[44:45]
	v_lshl_add_u64 v[126:127], v[126:127], 3, s[44:45]
	v_ashrrev_i32_e32 v219, 31, v218
	v_mfma_f32_16x16x32_f16 v[86:89], v[14:17], v[128:131], v[86:89]
	v_ashrrev_i32_e32 v221, 31, v220
	v_mfma_f32_16x16x32_f16 v[116:119], v[26:29], v[132:135], v[116:119]
	v_lshl_add_u64 v[132:133], v[214:215], 3, s[44:45]
	global_load_dwordx2 v[240:241], v[124:125], off
	global_load_dwordx2 v[242:243], v[126:127], off
	global_load_dwordx2 v[244:245], v[132:133], off
	global_load_dwordx2 v[246:247], v[124:125], off offset:2048
	s_nop 4
	v_pk_mul_f32 v[120:121], v[112:113], v[86:87]
	v_pk_mul_f32 v[86:87], v[82:83], v[86:87]
	v_pk_mul_f32 v[122:123], v[114:115], v[88:89]
	v_pk_mul_f32 v[88:89], v[136:137], v[88:89]
	v_pk_fma_f32 v[82:83], v[82:83], v[116:117], v[120:121] neg_lo:[0,0,1] neg_hi:[0,0,1]
	v_pk_fma_f32 v[86:87], v[112:113], v[116:117], v[86:87]
	v_pk_fma_f32 v[112:113], v[136:137], v[118:119], v[122:123] neg_lo:[0,0,1] neg_hi:[0,0,1]
	v_pk_fma_f32 v[88:89], v[114:115], v[118:119], v[88:89]
	v_cvt_pk_f16_f32 v82, v82, v83
	v_cvt_pk_f16_f32 v83, v112, v113
	v_cvt_pk_f16_f32 v86, v86, v87
	v_cvt_pk_f16_f32 v87, v88, v89
	ds_write_b64 v111, v[82:83]
	ds_write_b64 v217, v[86:87]
	ds_read_b64_tr_b16 v[86:87], v85 offset:32
	ds_read_b64_tr_b16 v[88:89], v85 offset:1120
	ds_read_b64_tr_b16 v[112:113], v85 offset:34848
	ds_read_b64_tr_b16 v[114:115], v85 offset:35936
	s_waitcnt lgkmcnt(2)
	v_mfma_f32_16x16x32_f16 v[116:119], v[54:57], v[86:89], 0
	s_nop 0
	s_nop 0
	v_ashrrev_i32_e32 v217, 31, v216
	v_lshl_add_u64 v[214:215], v[216:217], 3, s[44:45]
	s_waitcnt lgkmcnt(0)
	v_mfma_f32_16x16x32_f16 v[120:123], v[54:57], v[112:115], 0
	v_lshl_add_u64 v[216:217], v[218:219], 3, s[44:45]
	v_lshl_add_u64 v[218:219], v[220:221], 3, s[44:45]
	v_add_u32_e32 v111, 0x1a900, v213
	v_mfma_f32_16x16x32_f16 v[112:115], v[50:53], v[112:115], v[116:119]
	s_nop 2
	ds_read_b64_tr_b16 v[116:117], v85 offset:8736
	v_mfma_f32_16x16x32_f16 v[86:89], v[2:5], v[86:89], v[120:123]
	ds_read_b64_tr_b16 v[118:119], v85 offset:9824
	s_nop 1
	ds_read_b64_tr_b16 v[120:121], v85 offset:43552
	ds_read_b64_tr_b16 v[122:123], v85 offset:44640
	s_nop 0
	s_nop 0
	s_nop 0
	s_waitcnt lgkmcnt(2)
	v_mfma_f32_16x16x32_f16 v[112:115], v[46:49], v[116:119], v[112:115]
	s_waitcnt lgkmcnt(0)
	v_mfma_f32_16x16x32_f16 v[86:89], v[46:49], v[120:123], v[86:89]
	v_mfma_f32_16x16x32_f16 v[112:115], v[42:45], v[120:123], v[112:115]
	ds_read_b64_tr_b16 v[120:121], v85 offset:17440
	ds_read_b64_tr_b16 v[122:123], v85 offset:18528
	ds_read_b64_tr_b16 v[124:125], v85 offset:52256
	ds_read_b64_tr_b16 v[126:127], v85 offset:53344
	v_mfma_f32_16x16x32_f16 v[86:89], v[6:9], v[116:119], v[86:89]
	s_waitcnt lgkmcnt(2)
	v_mfma_f32_16x16x32_f16 v[128:131], v[38:41], v[120:123], v[112:115]
	global_load_dwordx2 v[118:119], v[214:215], off
	global_load_dwordx2 v[116:117], v[214:215], off offset:2048
	s_nop 0
	global_load_dwordx2 v[112:113], v[216:217], off
	global_load_dwordx2 v[114:115], v[218:219], off
	s_waitcnt lgkmcnt(0)
	v_mfma_f32_16x16x32_f16 v[86:89], v[38:41], v[124:127], v[86:89]
	v_mfma_f32_16x16x32_f16 v[124:127], v[34:37], v[124:127], v[128:131]
	s_nop 2
	ds_read_b64_tr_b16 v[128:129], v85 offset:26144
	v_mfma_f32_16x16x32_f16 v[86:89], v[10:13], v[120:123], v[86:89]
	ds_read_b64_tr_b16 v[130:131], v85 offset:27232
	ds_read_b64_tr_b16 v[120:121], v85 offset:60960
	ds_read_b64_tr_b16 v[122:123], v85 offset:62048
	v_add_u32_e32 v85, 0x12100, v213
	s_waitcnt lgkmcnt(0)
	v_mfma_f32_16x16x32_f16 v[86:89], v[30:33], v[120:123], v[86:89]
	v_mfma_f32_16x16x32_f16 v[124:127], v[30:33], v[128:131], v[124:127]
	v_mfma_f32_16x16x32_f16 v[86:89], v[14:17], v[128:131], v[86:89]
	v_mfma_f32_16x16x32_f16 v[120:123], v[26:29], v[120:123], v[124:127]
	s_waitcnt vmcnt(7)
	s_nop 4
	v_mov_b32_e32 v124, v240
	s_waitcnt vmcnt(6)
	v_mov_b32_e32 v125, v242
	v_mov_b32_e32 v134, v241
	v_mov_b32_e32 v135, v243
	v_pk_mul_f32 v[126:127], v[134:135], v[86:87]
	v_pk_mul_f32 v[86:87], v[124:125], v[86:87]
	v_pk_fma_f32 v[124:125], v[124:125], v[120:121], v[126:127] neg_lo:[0,0,1] neg_hi:[0,0,1]
	v_pk_fma_f32 v[86:87], v[134:135], v[120:121], v[86:87]
	v_cvt_pk_f16_f32 v120, v124, v125
	v_cvt_pk_f16_f32 v86, v86, v87
	s_waitcnt vmcnt(5)
	v_mov_b32_e32 v83, v244
	s_waitcnt vmcnt(4)
	v_mov_b32_e32 v132, v247
	v_mov_b32_e32 v133, v245
	v_mov_b32_e32 v82, v246
	v_pk_mul_f32 v[128:129], v[132:133], v[88:89]
	v_pk_mul_f32 v[88:89], v[82:83], v[88:89]
	v_pk_fma_f32 v[82:83], v[82:83], v[122:123], v[128:129] neg_lo:[0,0,1] neg_hi:[0,0,1]
	v_pk_fma_f32 v[88:89], v[132:133], v[122:123], v[88:89]
	v_cvt_pk_f16_f32 v121, v82, v83
	v_cvt_pk_f16_f32 v87, v88, v89
	ds_write_b64 v85, v[120:121]
	ds_write_b64 v111, v[86:87]
	s_cbranch_scc0 .LBB0_555
